# stack j + dead identity rotation also removed from the ukv GEMM epilogue (rope_pn -1 there as well)
# baseline (speedup 1.0000x reference)
; __device__ __forceinline__ unsigned cvt_pk_bf16(float lo, float hi) { unsigned r; asm("v_cvt_pk_bf16_f32 %0, %1, %2" : "=v"(r) : "v"(lo), "v"(hi)); return r; }
;     __device__ __forceinline__ void operator()(AccRef acc, const pg8::Unit& u, int wr, int wc, int fr, int fq) const {
;         const int row0 = u.pm * 256 + wr * 64 + fr, col0 = u.pn * 256 + wc * 32 + 4 * fq;
;         const bool rope = (u.pn == rope_pn) && (u.pm < 32);
; #pragma unroll
;         for (int ai = 0; ai < 2; ++ai)
; #pragma unroll
;             for (int m = 0; m < 4; ++m) { const int row = row0 + ai * 128 + m * 16; bf16_t* rowp = O + (size_t)row * ldc + col0;
;                 f32x4 cs = {1.f, 1.f, 1.f, 1.f}, sn = {0.f, 0.f, 0.f, 0.f};
;                 if (rope) { const int t = row & 2047; const int pos = (wc & 1) ? (t & 63) : (t >> 6); cs = *(const f32x4*)(cos64 + pos * 16 + 4 * fq); sn = *(const f32x4*)(sin64 + pos * 16 + 4 * fq); }
; #pragma unroll
;                 for (int bj = 0; bj < 2; ++bj) {
;                     const f32x4 x0 = acc[ai][bj][m][0], x1 = acc[ai][bj][m][1];
;                     const f32x4 y0 = x0 * cs - x1 * sn, y1 = x1 * cs + x0 * sn;
;                     u32x2 w0, w1; w0.x = cvt_pk_bf16(y0[0], y0[1]); w0.y = cvt_pk_bf16(y0[2], y0[3]); w1.x = cvt_pk_bf16(y1[0], y1[1]); w1.y = cvt_pk_bf16(y1[2], y1[3]);
;                     *(u32x2*)(rowp + bj * 128) = w0; *(u32x2*)(rowp + bj * 128 + 16) = w1; } }
;     }
.LBB0_3302:
	v_lshlrev_b64 v[16:17], 11, v[152:153]
	v_lshl_add_u64 v[16:17], s[70:71], 0, v[16:17]
	s_waitcnt vmcnt(0)
	v_lshl_add_u64 v[16:17], v[150:151], 1, v[16:17]
	s_mov_b32 s1, 0x58000
	v_cvt_pk_bf16_f32 v8, v8, v9
	v_cvt_pk_bf16_f32 v9, v10, v11
	v_add_co_u32_e32 v10, vcc, s1, v16
	s_mov_b64 s[28:29], 0x58000
	v_cvt_pk_bf16_f32 v12, v12, v13
	v_cvt_pk_bf16_f32 v13, v14, v15
	v_addc_co_u32_e32 v11, vcc, 0, v17, vcc
	v_lshl_add_u64 v[18:19], v[16:17], 0, s[28:29]
	global_store_dwordx2 v[10:11], v[12:13], off
	global_store_dwordx2 v[18:19], v[8:9], off offset:32
	v_cvt_pk_bf16_f32 v4, v4, v5
	v_cvt_pk_bf16_f32 v5, v6, v7
	s_and_b64 vcc, exec, s[40:41]
	s_mov_b32 s27, s0
	s_mov_b32 s28, s2
	s_mov_b64 s[42:43], s[48:49]
	s_mov_b64 s[50:51], s[46:47]
	v_cvt_pk_bf16_f32 v0, v0, v1
	s_nop 0
	v_cvt_pk_bf16_f32 v1, v2, v3
	global_store_dwordx2 v[18:19], v[4:5], off offset:256
	global_store_dwordx2 v[18:19], v[0:1], off offset:288
	s_cbranch_vccnz .LBB0_3323

; __device__ __forceinline__ unsigned cvt_pk_bf16(float lo, float hi) { unsigned r; asm("v_cvt_pk_bf16_f32 %0, %1, %2" : "=v"(r) : "v"(lo), "v"(hi)); return r; }
;     __device__ __forceinline__ void operator()(AccRef acc, const pg8::Unit& u, int wr, int wc, int fr, int fq) const {
;         const int row0 = u.pm * 256 + wr * 64 + fr, col0 = u.pn * 256 + wc * 32 + 4 * fq;
;         const bool rope = (u.pn == rope_pn) && (u.pm < 32);
; #pragma unroll
;         for (int ai = 0; ai < 2; ++ai)
; #pragma unroll
;             for (int m = 0; m < 4; ++m) { const int row = row0 + ai * 128 + m * 16; bf16_t* rowp = O + (size_t)row * ldc + col0;
;                 f32x4 cs = {1.f, 1.f, 1.f, 1.f}, sn = {0.f, 0.f, 0.f, 0.f};
;                 if (rope) { const int t = row & 2047; const int pos = (wc & 1) ? (t & 63) : (t >> 6); cs = *(const f32x4*)(cos64 + pos * 16 + 4 * fq); sn = *(const f32x4*)(sin64 + pos * 16 + 4 * fq); }
; #pragma unroll
;                 for (int bj = 0; bj < 2; ++bj) {
;                     const f32x4 x0 = acc[ai][bj][m][0], x1 = acc[ai][bj][m][1];
;                     const f32x4 y0 = x0 * cs - x1 * sn, y1 = x1 * cs + x0 * sn;
;                     u32x2 w0, w1; w0.x = cvt_pk_bf16(y0[0], y0[1]); w0.y = cvt_pk_bf16(y0[2], y0[3]); w1.x = cvt_pk_bf16(y1[0], y1[1]); w1.y = cvt_pk_bf16(y1[2], y1[3]);
;                     *(u32x2*)(rowp + bj * 128) = w0; *(u32x2*)(rowp + bj * 128 + 16) = w1; } }
;     }
.LBB0_3309:
	v_or_b32_e32 v152, s3, v154
	v_ashrrev_i32_e32 v153, 31, v152
	v_lshl_or_b32 v150, s27, 8, v159
	v_lshlrev_b64 v[130:131], 11, v[152:153]
	s_waitcnt vmcnt(0)
	v_ashrrev_i32_e32 v151, 31, v150
	v_lshl_add_u64 v[130:131], s[70:71], 0, v[130:131]
	v_lshl_add_u64 v[130:131], v[150:151], 1, v[130:131]
	v_cvt_pk_bf16_f32 v124, v124, v125
	v_cvt_pk_bf16_f32 v125, v126, v127
	v_cvt_pk_bf16_f32 v120, v120, v121
	s_and_b64 vcc, exec, s[42:43]
	v_cvt_pk_bf16_f32 v121, v122, v123
	global_store_dwordx2 v[130:131], v[124:125], off
	global_store_dwordx2 v[130:131], v[120:121], off offset:32
	v_cvt_pk_bf16_f32 v116, v116, v117
	v_cvt_pk_bf16_f32 v117, v118, v119
	v_cvt_pk_bf16_f32 v112, v112, v113
	v_mov_b32_e32 v133, 0
	v_cvt_pk_bf16_f32 v113, v114, v115
	global_store_dwordx2 v[130:131], v[116:117], off offset:256
	global_store_dwordx2 v[130:131], v[112:113], off offset:288
	v_mov_b32_e32 v134, 0
	v_mov_b32_e32 v135, 0
	v_mov_b32_e32 v129, 1.0
	v_mov_b32_e32 v130, 1.0
	v_mov_b32_e32 v131, 1.0
	s_cbranch_vccnz .LBB0_3311
	v_mov_b32_e32 v112, s1
	v_cndmask_b32_e64 v112, v156, v112, s[38:39]
	v_lshlrev_b32_e32 v178, 6, v112
	v_lshl_add_u64 v[112:113], v[148:149], 0, v[178:179]
	v_lshl_add_u64 v[114:115], v[146:147], 0, v[178:179]
	global_load_dwordx4 v[128:131], v[112:113], off
	global_load_dwordx4 v[132:135], v[114:115], off
.LBB0_3311:
	v_or_b32_e32 v112, 16, v152
	v_ashrrev_i32_e32 v113, 31, v112
	v_lshlrev_b64 v[112:113], 11, v[112:113]
	s_waitcnt vmcnt(0)
	v_lshl_add_u64 v[112:113], s[70:71], 0, v[112:113]
	v_lshl_add_u64 v[112:113], v[150:151], 1, v[112:113]
	v_cvt_pk_bf16_f32 v108, v108, v109
	v_cvt_pk_bf16_f32 v109, v110, v111
	v_cvt_pk_bf16_f32 v104, v104, v105
	v_cvt_pk_bf16_f32 v105, v106, v107
	global_store_dwordx2 v[112:113], v[108:109], off
	global_store_dwordx2 v[112:113], v[104:105], off offset:32
	v_cvt_pk_bf16_f32 v100, v100, v101
	v_cvt_pk_bf16_f32 v101, v102, v103
	v_cvt_pk_bf16_f32 v96, v96, v97
	s_and_b64 vcc, exec, s[42:43]
	v_mov_b32_e32 v102, 0
	v_cvt_pk_bf16_f32 v97, v98, v99
	global_store_dwordx2 v[112:113], v[100:101], off offset:256
	global_store_dwordx2 v[112:113], v[96:97], off offset:288
	v_mov_b32_e32 v96, 1.0
	v_mov_b32_e32 v100, 0
	v_mov_b32_e32 v103, 0
	v_mov_b32_e32 v104, 0
	v_mov_b32_e32 v105, 0
	v_mov_b32_e32 v106, 1.0
	v_mov_b32_e32 v107, 1.0
	v_mov_b32_e32 v108, 1.0
	v_mov_b32_e32 v109, 1.0
	s_cbranch_vccnz .LBB0_3313
	v_mov_b32_e32 v97, s1
	v_cndmask_b32_e64 v97, v157, v97, s[38:39]
	v_lshlrev_b32_e32 v178, 6, v97
	v_lshl_add_u64 v[98:99], v[148:149], 0, v[178:179]
	v_lshl_add_u64 v[102:103], v[146:147], 0, v[178:179]
	global_load_dwordx4 v[106:109], v[98:99], off
	s_nop 0
	global_load_dwordx4 v[102:105], v[102:103], off
.LBB0_3313:
	v_or_b32_e32 v98, 32, v152
	v_ashrrev_i32_e32 v99, 31, v98
	v_lshlrev_b64 v[98:99], 11, v[98:99]
	s_waitcnt vmcnt(0)
	v_lshl_add_u64 v[98:99], s[70:71], 0, v[98:99]
	v_lshl_add_u64 v[98:99], v[150:151], 1, v[98:99]
	v_cvt_pk_bf16_f32 v92, v92, v93
	v_cvt_pk_bf16_f32 v93, v94, v95
	v_cvt_pk_bf16_f32 v88, v88, v89
	s_and_b64 vcc, exec, s[42:43]
	v_cvt_pk_bf16_f32 v89, v90, v91
	global_store_dwordx2 v[98:99], v[92:93], off
	global_store_dwordx2 v[98:99], v[88:89], off offset:32
	v_cvt_pk_bf16_f32 v84, v84, v85
	v_cvt_pk_bf16_f32 v85, v86, v87
	v_cvt_pk_bf16_f32 v80, v80, v81
	v_mov_b32_e32 v101, 0
	v_cvt_pk_bf16_f32 v81, v82, v83
	global_store_dwordx2 v[98:99], v[84:85], off offset:256
	global_store_dwordx2 v[98:99], v[80:81], off offset:288
	v_mov_b32_e32 v102, 0
	v_mov_b32_e32 v103, 0
	v_mov_b32_e32 v97, 1.0
	v_mov_b32_e32 v98, 1.0
	v_mov_b32_e32 v99, 1.0
	s_mov_b64 s[72:73], s[78:79]
	v_readlane_b32 s64, v255, 53
	v_readlane_b32 s63, v255, 55
	v_readlane_b32 s65, v255, 54
	s_cbranch_vccnz .LBB0_3315
	v_mov_b32_e32 v80, s1
	v_cndmask_b32_e64 v80, v158, v80, s[38:39]
	v_lshlrev_b32_e32 v178, 6, v80
	v_lshl_add_u64 v[80:81], v[148:149], 0, v[178:179]
	v_lshl_add_u64 v[82:83], v[146:147], 0, v[178:179]
	global_load_dwordx4 v[96:99], v[80:81], off
	global_load_dwordx4 v[100:103], v[82:83], off
; __device__ __forceinline__ unsigned cvt_pk_bf16(float lo, float hi) { unsigned r; asm("v_cvt_pk_bf16_f32 %0, %1, %2" : "=v"(r) : "v"(lo), "v"(hi)); return r; }
;     __device__ __forceinline__ void operator()(AccRef acc, const pg8::Unit& u, int wr, int wc, int fr, int fq) const {
;         const int row0 = u.pm * 256 + wr * 64 + fr, col0 = u.pn * 256 + wc * 32 + 4 * fq;
;         const bool rope = (u.pn == rope_pn) && (u.pm < 32);
; #pragma unroll
;         for (int ai = 0; ai < 2; ++ai)
; #pragma unroll
;             for (int m = 0; m < 4; ++m) { const int row = row0 + ai * 128 + m * 16; bf16_t* rowp = O + (size_t)row * ldc + col0;
;                 f32x4 cs = {1.f, 1.f, 1.f, 1.f}, sn = {0.f, 0.f, 0.f, 0.f};
;                 if (rope) { const int t = row & 2047; const int pos = (wc & 1) ? (t & 63) : (t >> 6); cs = *(const f32x4*)(cos64 + pos * 16 + 4 * fq); sn = *(const f32x4*)(sin64 + pos * 16 + 4 * fq); }
; #pragma unroll
;                 for (int bj = 0; bj < 2; ++bj) {
;                     const f32x4 x0 = acc[ai][bj][m][0], x1 = acc[ai][bj][m][1];
;                     const f32x4 y0 = x0 * cs - x1 * sn, y1 = x1 * cs + x0 * sn;
;                     u32x2 w0, w1; w0.x = cvt_pk_bf16(y0[0], y0[1]); w0.y = cvt_pk_bf16(y0[2], y0[3]); w1.x = cvt_pk_bf16(y1[0], y1[1]); w1.y = cvt_pk_bf16(y1[2], y1[3]);
;                     *(u32x2*)(rowp + bj * 128) = w0; *(u32x2*)(rowp + bj * 128 + 16) = w1; } }
;     }
.LBB0_3315:
	v_or_b32_e32 v80, 48, v152
	v_ashrrev_i32_e32 v81, 31, v80
	v_lshlrev_b64 v[80:81], 11, v[80:81]
	s_waitcnt vmcnt(0)
	v_lshl_add_u64 v[80:81], s[70:71], 0, v[80:81]
	v_lshl_add_u64 v[80:81], v[150:151], 1, v[80:81]
	v_cvt_pk_bf16_f32 v76, v76, v77
	v_cvt_pk_bf16_f32 v77, v78, v79
	v_cvt_pk_bf16_f32 v72, v72, v73
	s_and_b64 vcc, exec, s[42:43]
	v_cvt_pk_bf16_f32 v73, v74, v75
	global_store_dwordx2 v[80:81], v[76:77], off
	global_store_dwordx2 v[80:81], v[72:73], off offset:32
	v_cvt_pk_bf16_f32 v68, v68, v69
	v_cvt_pk_bf16_f32 v69, v70, v71
	v_cvt_pk_bf16_f32 v64, v64, v65
	v_cvt_pk_bf16_f32 v65, v66, v67
	v_add_u32_e32 v66, 0x80, v152
	global_store_dwordx2 v[80:81], v[68:69], off offset:256
	global_store_dwordx2 v[80:81], v[64:65], off offset:288
	v_bfe_u32 v78, v66, 6, 5
	v_mov_b32_e32 v64, 1.0
	v_mov_b32_e32 v68, 0
	v_mov_b32_e32 v70, 0
	v_mov_b32_e32 v71, 0
	v_mov_b32_e32 v72, 0
	v_mov_b32_e32 v73, 0
	v_mov_b32_e32 v74, 1.0
	v_mov_b32_e32 v75, 1.0
	v_mov_b32_e32 v76, 1.0
	v_mov_b32_e32 v77, 1.0
	s_cbranch_vccnz .LBB0_3317
	v_cndmask_b32_e64 v65, v154, v78, s[38:39]
	v_lshlrev_b32_e32 v178, 6, v65
	v_lshl_add_u64 v[70:71], v[148:149], 0, v[178:179]
	v_lshl_add_u64 v[72:73], v[146:147], 0, v[178:179]
	global_load_dwordx4 v[74:77], v[70:71], off
	s_nop 0
	global_load_dwordx4 v[70:73], v[72:73], off
.LBB0_3317:
	v_ashrrev_i32_e32 v67, 31, v66
	v_lshlrev_b64 v[66:67], 11, v[66:67]
	s_waitcnt vmcnt(0)
	v_lshl_add_u64 v[66:67], s[70:71], 0, v[66:67]
	v_lshl_add_u64 v[66:67], v[150:151], 1, v[66:67]
	v_cvt_pk_bf16_f32 v60, v60, v61
	v_cvt_pk_bf16_f32 v61, v62, v63
	v_cvt_pk_bf16_f32 v56, v56, v57
	s_and_b64 vcc, exec, s[42:43]
	v_cvt_pk_bf16_f32 v57, v58, v59
	global_store_dwordx2 v[66:67], v[60:61], off
	global_store_dwordx2 v[66:67], v[56:57], off offset:32
	v_cvt_pk_bf16_f32 v52, v52, v53
	v_cvt_pk_bf16_f32 v53, v54, v55
	v_cvt_pk_bf16_f32 v48, v48, v49
	v_mov_b32_e32 v69, 0
	v_cvt_pk_bf16_f32 v49, v50, v51
	global_store_dwordx2 v[66:67], v[52:53], off offset:256
	global_store_dwordx2 v[66:67], v[48:49], off offset:288
	v_mov_b32_e32 v70, 0
	v_mov_b32_e32 v71, 0
	v_mov_b32_e32 v65, 1.0
	v_mov_b32_e32 v66, 1.0
	v_mov_b32_e32 v67, 1.0
	s_cbranch_vccnz .LBB0_3319
	v_cndmask_b32_e64 v48, v156, v78, s[38:39]
	v_lshlrev_b32_e32 v178, 6, v48
	v_lshl_add_u64 v[48:49], v[148:149], 0, v[178:179]
	v_lshl_add_u64 v[50:51], v[146:147], 0, v[178:179]
	global_load_dwordx4 v[64:67], v[48:49], off
	global_load_dwordx4 v[68:71], v[50:51], off
.LBB0_3319:
	v_lshlrev_b64 v[48:49], 11, v[152:153]
	v_lshl_add_u64 v[48:49], s[70:71], 0, v[48:49]
	s_waitcnt vmcnt(0)
	v_lshl_add_u64 v[48:49], v[150:151], 1, v[48:49]
	s_mov_b32 s1, 0x48000
	v_cvt_pk_bf16_f32 v40, v40, v41
	v_cvt_pk_bf16_f32 v41, v42, v43
	v_add_co_u32_e32 v42, vcc, s1, v48
	s_mov_b64 s[28:29], 0x48000
	v_cvt_pk_bf16_f32 v44, v44, v45
	v_cvt_pk_bf16_f32 v45, v46, v47
	v_addc_co_u32_e32 v43, vcc, 0, v49, vcc
	v_lshl_add_u64 v[50:51], v[48:49], 0, s[28:29]
	global_store_dwordx2 v[42:43], v[44:45], off
	global_store_dwordx2 v[50:51], v[40:41], off offset:32
	v_cvt_pk_bf16_f32 v36, v36, v37
	v_cvt_pk_bf16_f32 v37, v38, v39
	v_cvt_pk_bf16_f32 v32, v32, v33
	s_and_b64 vcc, exec, s[42:43]
	v_mov_b32_e32 v38, 0
	v_cvt_pk_bf16_f32 v33, v34, v35
	global_store_dwordx2 v[50:51], v[36:37], off offset:256
	global_store_dwordx2 v[50:51], v[32:33], off offset:288
	v_mov_b32_e32 v32, 1.0
	v_mov_b32_e32 v36, 0
	v_mov_b32_e32 v39, 0
	v_mov_b32_e32 v40, 0
	v_mov_b32_e32 v41, 0
	v_mov_b32_e32 v42, 1.0
	v_mov_b32_e32 v43, 1.0
	v_mov_b32_e32 v44, 1.0
	v_mov_b32_e32 v45, 1.0
	s_cbranch_vccnz .LBB0_3321
	v_cndmask_b32_e64 v33, v157, v78, s[38:39]
	v_lshlrev_b32_e32 v178, 6, v33
	v_lshl_add_u64 v[34:35], v[148:149], 0, v[178:179]
	v_lshl_add_u64 v[38:39], v[146:147], 0, v[178:179]
	global_load_dwordx4 v[42:45], v[34:35], off
	s_nop 0
	global_load_dwordx4 v[38:41], v[38:39], off
.LBB0_3321:
	s_waitcnt vmcnt(0)
	s_mov_b32 s1, 0x50000
	v_cvt_pk_bf16_f32 v24, v24, v25
	v_cvt_pk_bf16_f32 v25, v26, v27
	v_add_co_u32_e32 v26, vcc, s1, v48
	s_mov_b64 s[28:29], 0x50000
	v_cvt_pk_bf16_f32 v28, v28, v29
	v_cvt_pk_bf16_f32 v29, v30, v31
	v_addc_co_u32_e32 v27, vcc, 0, v49, vcc
	v_lshl_add_u64 v[34:35], v[48:49], 0, s[28:29]
	global_store_dwordx2 v[26:27], v[28:29], off
	global_store_dwordx2 v[34:35], v[24:25], off offset:32
	v_cvt_pk_bf16_f32 v20, v20, v21
	v_cvt_pk_bf16_f32 v21, v22, v23
	v_cvt_pk_bf16_f32 v16, v16, v17
	s_and_b64 vcc, exec, s[42:43]
	v_cvt_pk_bf16_f32 v17, v18, v19
	global_store_dwordx2 v[34:35], v[20:21], off offset:256
	global_store_dwordx2 v[34:35], v[16:17], off offset:288
	v_mov_b32_e32 v37, 0
	v_mov_b32_e32 v38, 0
	v_mov_b32_e32 v39, 0
	v_mov_b32_e32 v33, 1.0
	v_mov_b32_e32 v34, 1.0
	v_mov_b32_e32 v35, 1.0
	s_cbranch_vccnz .LBB0_3302
	v_cndmask_b32_e64 v16, v158, v78, s[38:39]
	v_lshlrev_b32_e32 v178, 6, v16
	v_lshl_add_u64 v[16:17], v[148:149], 0, v[178:179]
	v_lshl_add_u64 v[18:19], v[146:147], 0, v[178:179]
	global_load_dwordx4 v[32:35], v[16:17], off
	global_load_dwordx4 v[36:39], v[18:19], off
	s_branch .LBB0_3302
